# attention epilogue: 8 subln-gamma loads issued up front instead of load/wait/store serial chain (both row halves)
# speedup vs baseline: 1.0176x; 1.0019x over previous
; DEVI void attn_item(const Params& p, int j, int h, int qt, float lam, float one_m_linit, char* smem) {
;     ...
;   if (c == 0) {
;     const float* sw = p.in[5] + j * 128;
;     bf16_t* cat = (bf16_t*)(p.ws + OFF_R1);
; #pragma unroll
;     for (int qi = 0; qi < 2; ++qi) {
;       float ss = 0.f;
; #pragma unroll
;       for (int d = 0; d < 8; ++d) {
;         f32x4 o1 = xb[((rg * 2 + qi) * 8 + d) * 64 + lane];
;         f32x4 o = oacc[qi][d] - o1 * lam;
;         oacc[qi][d] = o;
;         ss += o[0] * o[0] + o[1] * o[1] + o[2] * o[2] + o[3] * o[3];
;       }
;       ss += __shfl_xor(ss, 16);
;       ss += __shfl_xor(ss, 32);
;       const float r = rsqrtf(ss * (1.f / 128.f) + 1e-6f) * one_m_linit;
;       const int qpos = qw + qi * 16 + l15;
;       if (qpos < L) {
; #pragma unroll
;         for (int d = 0; d < 8; ++d) {
;           const int dv = d * 16 + quad * 4;
;           f32x4 w = *(const f32x4*)(sw + dv);
;           f32x4 o = oacc[qi][d] * r * w;
;           *(u32x2*)(cat + (size_t)qpos * 1024 + h * 128 + dv) = u32x2{pack2(o[0], o[1]), pack2(o[2], o[3])};
.LBB0_247:
	s_or_b64 exec, exec, s[0:1]
	v_cmp_gt_u32_e32 vcc, s49, v228
	s_waitcnt lgkmcnt(0)
	s_barrier
	s_and_saveexec_b64 s[0:1], vcc
	s_cbranch_execz .LBB0_75
	v_and_b32_e32 v67, 64, v215
	v_xor_b32_e32 v66, 16, v215
	v_add_u32_e32 v67, 64, v67
	v_cmp_lt_i32_e32 vcc, v66, v67
	v_xor_b32_e32 v69, 32, v215
	s_xor_b32 s7, s34, 0x80000000
	v_cndmask_b32_e32 v66, v215, v66, vcc
	v_cmp_lt_i32_e32 vcc, v69, v67
	s_xor_b32 s6, s13, 0x80000000
	v_lshlrev_b32_e32 v66, 2, v66
	v_cndmask_b32_e32 v67, v215, v69, vcc
	v_lshlrev_b32_e32 v69, 14, v68
	v_add3_u32 v69, 32, v69, v0
	ds_read_b128 v[72:75], v69
	v_lshl_or_b32 v68, v68, 10, v228
	v_lshlrev_b32_e32 v68, 4, v68
	v_or_b32_e32 v70, 0x400, v68
	v_add_u32_e32 v70, 32, v70
	s_waitcnt lgkmcnt(0)
	v_pk_fma_f32 v[64:65], s[6:7], v[74:75], v[64:65]
	v_pk_fma_f32 v[62:63], s[46:47], v[72:73], v[62:63] neg_lo:[1,0,0] neg_hi:[1,0,0]
	ds_read_b128 v[72:75], v70
	v_mul_f32_e32 v0, v63, v63
	v_fmac_f32_e32 v0, v62, v62
	v_fmac_f32_e32 v0, v64, v64
	v_fmac_f32_e32 v0, v65, v65
	s_waitcnt lgkmcnt(0)
	v_pk_fma_f32 v[60:61], s[6:7], v[74:75], v[60:61]
	v_pk_fma_f32 v[58:59], s[46:47], v[72:73], v[58:59] neg_lo:[1,0,0] neg_hi:[1,0,0]
	ds_read_b128 v[72:75], v69 offset:2048
	v_mul_f32_e32 v70, v59, v59
	v_fmac_f32_e32 v70, v58, v58
	v_fmac_f32_e32 v70, v60, v60
	v_fmac_f32_e32 v70, v61, v61
	s_waitcnt lgkmcnt(0)
	v_pk_fma_f32 v[54:55], s[46:47], v[72:73], v[54:55] neg_lo:[1,0,0] neg_hi:[1,0,0]
	v_add_f32_e32 v0, v0, v70
	v_mul_f32_e32 v70, v55, v55
	v_pk_fma_f32 v[56:57], s[6:7], v[74:75], v[56:57]
	v_fmac_f32_e32 v70, v54, v54
	v_fmac_f32_e32 v70, v56, v56
	v_fmac_f32_e32 v70, v57, v57
	v_add_f32_e32 v0, v0, v70
	v_or_b32_e32 v70, 0xc00, v68
	v_add_u32_e32 v70, 32, v70
	ds_read_b128 v[72:75], v70
	v_lshlrev_b32_e32 v67, 2, v67
	v_lshlrev_b32_e32 v71, 2, v231
	s_movk_i32 s5, 0x4010
	v_cmp_gt_i32_e32 vcc, s5, v194
	s_waitcnt lgkmcnt(0)
	v_pk_fma_f32 v[52:53], s[6:7], v[74:75], v[52:53]
	v_pk_fma_f32 v[50:51], s[46:47], v[72:73], v[50:51] neg_lo:[1,0,0] neg_hi:[1,0,0]
	ds_read_b128 v[72:75], v69 offset:4096
	v_mul_f32_e32 v70, v51, v51
	v_fmac_f32_e32 v70, v50, v50
	v_fmac_f32_e32 v70, v52, v52
	v_fmac_f32_e32 v70, v53, v53
	s_waitcnt lgkmcnt(0)
	v_pk_fma_f32 v[46:47], s[46:47], v[72:73], v[46:47] neg_lo:[1,0,0] neg_hi:[1,0,0]
	v_add_f32_e32 v0, v0, v70
	v_mul_f32_e32 v70, v47, v47
	v_pk_fma_f32 v[48:49], s[6:7], v[74:75], v[48:49]
	v_fmac_f32_e32 v70, v46, v46
	v_fmac_f32_e32 v70, v48, v48
	v_fmac_f32_e32 v70, v49, v49
	v_add_f32_e32 v0, v0, v70
	v_or_b32_e32 v70, 0x1400, v68
	v_add_u32_e32 v70, 32, v70
	ds_read_b128 v[72:75], v70
	s_waitcnt lgkmcnt(0)
	v_pk_fma_f32 v[44:45], s[6:7], v[74:75], v[44:45]
	v_pk_fma_f32 v[42:43], s[46:47], v[72:73], v[42:43] neg_lo:[1,0,0] neg_hi:[1,0,0]
	ds_read_b128 v[72:75], v69 offset:6144
	v_mul_f32_e32 v70, v43, v43
	v_fmac_f32_e32 v70, v42, v42
	v_fmac_f32_e32 v70, v44, v44
	v_fmac_f32_e32 v70, v45, v45
	s_waitcnt lgkmcnt(0)
	v_pk_fma_f32 v[38:39], s[46:47], v[72:73], v[38:39] neg_lo:[1,0,0] neg_hi:[1,0,0]
	v_add_f32_e32 v0, v0, v70
	v_mul_f32_e32 v70, v39, v39
	v_pk_fma_f32 v[40:41], s[6:7], v[74:75], v[40:41]
	v_fmac_f32_e32 v70, v38, v38
	v_fmac_f32_e32 v70, v40, v40
	v_fmac_f32_e32 v70, v41, v41
	v_add_f32_e32 v0, v0, v70
	v_or_b32_e32 v70, 0x1c00, v68
	v_add_u32_e32 v70, 32, v70
	ds_read_b128 v[72:75], v70
	s_waitcnt lgkmcnt(0)
	v_pk_fma_f32 v[34:35], s[46:47], v[72:73], v[34:35] neg_lo:[1,0,0] neg_hi:[1,0,0]
	s_nop 0
	v_mul_f32_e32 v70, v35, v35
	v_pk_fma_f32 v[36:37], s[6:7], v[74:75], v[36:37]
	v_fmac_f32_e32 v70, v34, v34
	v_fmac_f32_e32 v70, v36, v36
	v_fmac_f32_e32 v70, v37, v37
	v_add_f32_e32 v0, v0, v70
	ds_bpermute_b32 v70, v66, v0
	s_waitcnt lgkmcnt(0)
	v_add_f32_e32 v72, v0, v70
	ds_bpermute_b32 v73, v67, v72
	v_lshlrev_b32_e32 v70, 2, v71
	v_lshlrev_b32_e32 v0, 1, v71
	s_and_saveexec_b64 s[10:11], vcc
	s_cbranch_execz .LBB0_250
	global_load_dwordx4 v[74:77], v70, s[16:17]
	global_load_dwordx4 v[144:147], v70, s[16:17] offset:64
	global_load_dwordx4 v[148:151], v70, s[16:17] offset:128
	global_load_dwordx4 v[152:155], v70, s[16:17] offset:192
	global_load_dwordx4 v[156:159], v70, s[16:17] offset:256
	global_load_dwordx4 v[160:163], v70, s[16:17] offset:320
	global_load_dwordx4 v[176:179], v70, s[16:17] offset:384
	global_load_dwordx4 v[180:183], v70, s[16:17] offset:448
	s_waitcnt lgkmcnt(0)
	v_add_f32_e32 v71, v72, v73
	v_fmamk_f32 v71, v71, 0x3c000000, v208
	v_mul_f32_e32 v72, 0x4b800000, v71
	v_cmp_gt_f32_e32 vcc, s2, v71
	s_nop 1
	v_cndmask_b32_e32 v71, v71, v72, vcc
	v_rsq_f32_e32 v71, v71
	v_lshlrev_b64 v[72:73], 11, v[194:195]
	v_lshl_add_u64 v[72:73], s[86:87], 0, v[72:73]
	v_lshl_add_u64 v[72:73], v[72:73], 0, v[0:1]
	v_mul_f32_e32 v78, 0x45800000, v71
	v_cndmask_b32_e32 v71, v71, v78, vcc
	v_mul_f32_e32 v78, v189, v71
	v_pk_mul_f32 v[62:63], v[62:63], v[78:79] op_sel_hi:[1,0]
	v_pk_mul_f32 v[64:65], v[64:65], v[78:79] op_sel_hi:[1,0]
	v_pk_mul_f32 v[58:59], v[58:59], v[78:79] op_sel_hi:[1,0]
	v_pk_mul_f32 v[60:61], v[60:61], v[78:79] op_sel_hi:[1,0]
	v_pk_mul_f32 v[54:55], v[54:55], v[78:79] op_sel_hi:[1,0]
	v_pk_mul_f32 v[56:57], v[56:57], v[78:79] op_sel_hi:[1,0]
	v_pk_mul_f32 v[50:51], v[50:51], v[78:79] op_sel_hi:[1,0]
	v_pk_mul_f32 v[52:53], v[52:53], v[78:79] op_sel_hi:[1,0]
	v_pk_mul_f32 v[46:47], v[46:47], v[78:79] op_sel_hi:[1,0]
	v_pk_mul_f32 v[48:49], v[48:49], v[78:79] op_sel_hi:[1,0]
	v_pk_mul_f32 v[42:43], v[42:43], v[78:79] op_sel_hi:[1,0]
	v_pk_mul_f32 v[44:45], v[44:45], v[78:79] op_sel_hi:[1,0]
	v_pk_mul_f32 v[38:39], v[38:39], v[78:79] op_sel_hi:[1,0]
	v_pk_mul_f32 v[40:41], v[40:41], v[78:79] op_sel_hi:[1,0]
	v_pk_mul_f32 v[34:35], v[34:35], v[78:79] op_sel_hi:[1,0]
	v_pk_mul_f32 v[36:37], v[36:37], v[78:79] op_sel_hi:[1,0]
	s_waitcnt vmcnt(0)
; DEVI void attn_item(const Params& p, int j, int h, int qt, float lam, float one_m_linit, char* smem) {
;     ...
; #pragma unroll
;         for (int d = 0; d < 8; ++d) {
;           const int dv = d * 16 + quad * 4;
;           f32x4 w = *(const f32x4*)(sw + dv);
;           f32x4 o = oacc[qi][d] * r * w;
;           *(u32x2*)(cat + (size_t)qpos * 1024 + h * 128 + dv) = u32x2{pack2(o[0], o[1]), pack2(o[2], o[3])};
;         }
	v_pk_mul_f32 v[64:65], v[64:65], v[76:77]
	v_pk_mul_f32 v[62:63], v[62:63], v[74:75]
	s_nop 0
	v_cvt_pk_bf16_f32 v62, v62, v63
	v_cvt_pk_bf16_f32 v63, v64, v65
	global_store_dwordx2 v[72:73], v[62:63], off
	v_pk_mul_f32 v[60:61], v[60:61], v[146:147]
	v_pk_mul_f32 v[58:59], v[58:59], v[144:145]
	s_nop 0
	v_cvt_pk_bf16_f32 v58, v58, v59
	v_cvt_pk_bf16_f32 v59, v60, v61
	global_store_dwordx2 v[72:73], v[58:59], off offset:32
	v_pk_mul_f32 v[56:57], v[56:57], v[150:151]
	v_pk_mul_f32 v[54:55], v[54:55], v[148:149]
	s_nop 0
	v_cvt_pk_bf16_f32 v54, v54, v55
	v_cvt_pk_bf16_f32 v55, v56, v57
	global_store_dwordx2 v[72:73], v[54:55], off offset:64
	v_pk_mul_f32 v[52:53], v[52:53], v[154:155]
	v_pk_mul_f32 v[50:51], v[50:51], v[152:153]
	s_nop 0
	v_cvt_pk_bf16_f32 v50, v50, v51
	v_cvt_pk_bf16_f32 v51, v52, v53
	global_store_dwordx2 v[72:73], v[50:51], off offset:96
	v_pk_mul_f32 v[48:49], v[48:49], v[158:159]
	v_pk_mul_f32 v[46:47], v[46:47], v[156:157]
	s_nop 0
	v_cvt_pk_bf16_f32 v46, v46, v47
	v_cvt_pk_bf16_f32 v47, v48, v49
	global_store_dwordx2 v[72:73], v[46:47], off offset:128
	v_pk_mul_f32 v[44:45], v[44:45], v[162:163]
	v_pk_mul_f32 v[42:43], v[42:43], v[160:161]
	s_nop 0
	v_cvt_pk_bf16_f32 v42, v42, v43
	v_cvt_pk_bf16_f32 v43, v44, v45
	global_store_dwordx2 v[72:73], v[42:43], off offset:160
	v_pk_mul_f32 v[40:41], v[40:41], v[178:179]
	v_pk_mul_f32 v[38:39], v[38:39], v[176:177]
	s_nop 0
	v_cvt_pk_bf16_f32 v38, v38, v39
	v_cvt_pk_bf16_f32 v39, v40, v41
	global_store_dwordx2 v[72:73], v[38:39], off offset:192
	v_pk_mul_f32 v[36:37], v[36:37], v[182:183]
	v_pk_mul_f32 v[34:35], v[34:35], v[180:181]
	s_nop 0
	v_cvt_pk_bf16_f32 v34, v34, v35
	v_cvt_pk_bf16_f32 v35, v36, v37
	global_store_dwordx2 v[72:73], v[34:35], off offset:224
; DEVI void attn_item(const Params& p, int j, int h, int qt, float lam, float one_m_linit, char* smem) {
;     ...
;     for (int qi = 0; qi < 2; ++qi) {
;       float ss = 0.f;
; #pragma unroll
;       for (int d = 0; d < 8; ++d) {
;         f32x4 o1 = xb[((rg * 2 + qi) * 8 + d) * 64 + lane];
;         f32x4 o = oacc[qi][d] - o1 * lam;
;         oacc[qi][d] = o;
;         ss += o[0] * o[0] + o[1] * o[1] + o[2] * o[2] + o[3] * o[3];
;       }
;       ss += __shfl_xor(ss, 16);
;       ss += __shfl_xor(ss, 32);
;       const float r = rsqrtf(ss * (1.f / 128.f) + 1e-6f) * one_m_linit;
;       const int qpos = qw + qi * 16 + l15;
;       if (qpos < L) {
; #pragma unroll
;         for (int d = 0; d < 8; ++d) {
;           const int dv = d * 16 + quad * 4;
;           f32x4 w = *(const f32x4*)(sw + dv);
;           f32x4 o = oacc[qi][d] * r * w;
;           *(u32x2*)(cat + (size_t)qpos * 1024 + h * 128 + dv) = u32x2{pack2(o[0], o[1]), pack2(o[2], o[3])};
;         }
;       }
.LBB0_250:
	s_or_b64 exec, exec, s[10:11]
	ds_read_b128 v[34:37], v69 offset:8192
	v_cmp_gt_i32_e32 vcc, s5, v192
	s_waitcnt lgkmcnt(0)
	v_pk_fma_f32 v[30:31], s[46:47], v[34:35], v[30:31] neg_lo:[1,0,0] neg_hi:[1,0,0]
	v_or_b32_e32 v34, 0x2400, v68
	v_add_u32_e32 v34, 32, v34
	v_pk_fma_f32 v[32:33], s[6:7], v[36:37], v[32:33]
	ds_read_b128 v[34:37], v34
	v_mul_f32_e32 v38, v31, v31
	v_fmac_f32_e32 v38, v30, v30
	v_fmac_f32_e32 v38, v32, v32
	v_fmac_f32_e32 v38, v33, v33
	s_waitcnt lgkmcnt(0)
	v_pk_fma_f32 v[26:27], s[46:47], v[34:35], v[26:27] neg_lo:[1,0,0] neg_hi:[1,0,0]
	v_pk_fma_f32 v[28:29], s[6:7], v[36:37], v[28:29]
	v_mul_f32_e32 v34, v27, v27
	v_fmac_f32_e32 v34, v26, v26
	v_fmac_f32_e32 v34, v28, v28
	v_fmac_f32_e32 v34, v29, v29
	v_add_f32_e32 v38, v38, v34
	ds_read_b128 v[34:37], v69 offset:10240
	s_waitcnt lgkmcnt(0)
	v_pk_fma_f32 v[22:23], s[46:47], v[34:35], v[22:23] neg_lo:[1,0,0] neg_hi:[1,0,0]
	s_nop 0
	v_mul_f32_e32 v34, v23, v23
	v_pk_fma_f32 v[24:25], s[6:7], v[36:37], v[24:25]
	v_fmac_f32_e32 v34, v22, v22
	v_fmac_f32_e32 v34, v24, v24
	v_fmac_f32_e32 v34, v25, v25
	v_add_f32_e32 v38, v38, v34
	v_or_b32_e32 v34, 0x2c00, v68
	v_add_u32_e32 v34, 32, v34
	ds_read_b128 v[34:37], v34
	s_waitcnt lgkmcnt(0)
	v_pk_fma_f32 v[18:19], s[46:47], v[34:35], v[18:19] neg_lo:[1,0,0] neg_hi:[1,0,0]
	s_nop 0
	v_mul_f32_e32 v34, v19, v19
	v_pk_fma_f32 v[20:21], s[6:7], v[36:37], v[20:21]
	v_fmac_f32_e32 v34, v18, v18
	v_fmac_f32_e32 v34, v20, v20
	v_fmac_f32_e32 v34, v21, v21
	v_add_f32_e32 v38, v38, v34
	ds_read_b128 v[34:37], v69 offset:12288
	s_waitcnt lgkmcnt(0)
	v_pk_fma_f32 v[14:15], s[46:47], v[34:35], v[14:15] neg_lo:[1,0,0] neg_hi:[1,0,0]
	s_nop 0
	v_mul_f32_e32 v34, v15, v15
	v_pk_fma_f32 v[16:17], s[6:7], v[36:37], v[16:17]
	v_fmac_f32_e32 v34, v14, v14
	v_fmac_f32_e32 v34, v16, v16
	v_fmac_f32_e32 v34, v17, v17
	v_add_f32_e32 v38, v38, v34
	v_or_b32_e32 v34, 0x3400, v68
	v_add_u32_e32 v34, 32, v34
	ds_read_b128 v[34:37], v34
	s_waitcnt lgkmcnt(0)
	v_pk_fma_f32 v[10:11], s[46:47], v[34:35], v[10:11] neg_lo:[1,0,0] neg_hi:[1,0,0]
	s_nop 0
	v_mul_f32_e32 v34, v11, v11
	v_pk_fma_f32 v[12:13], s[6:7], v[36:37], v[12:13]
	v_fmac_f32_e32 v34, v10, v10
	v_fmac_f32_e32 v34, v12, v12
	v_fmac_f32_e32 v34, v13, v13
	v_add_f32_e32 v38, v38, v34
	ds_read_b128 v[34:37], v69 offset:14336
	s_waitcnt lgkmcnt(0)
	v_pk_fma_f32 v[6:7], s[46:47], v[34:35], v[6:7] neg_lo:[1,0,0] neg_hi:[1,0,0]
	s_nop 0
	v_mul_f32_e32 v34, v7, v7
	v_pk_fma_f32 v[8:9], s[6:7], v[36:37], v[8:9]
	v_fmac_f32_e32 v34, v6, v6
	v_fmac_f32_e32 v34, v8, v8
	v_fmac_f32_e32 v34, v9, v9
	v_add_f32_e32 v38, v38, v34
	v_or_b32_e32 v34, 0x3c00, v68
	v_add_u32_e32 v34, 32, v34
	ds_read_b128 v[34:37], v34
	s_waitcnt lgkmcnt(0)
	v_pk_fma_f32 v[2:3], s[46:47], v[34:35], v[2:3] neg_lo:[1,0,0] neg_hi:[1,0,0]
	s_nop 0
	v_mul_f32_e32 v34, v3, v3
	v_pk_fma_f32 v[4:5], s[6:7], v[36:37], v[4:5]
	v_fmac_f32_e32 v34, v2, v2
	v_fmac_f32_e32 v34, v4, v4
	v_fmac_f32_e32 v34, v5, v5
	v_add_f32_e32 v34, v38, v34
	ds_bpermute_b32 v35, v66, v34
	s_waitcnt lgkmcnt(0)
	v_add_f32_e32 v34, v34, v35
	ds_bpermute_b32 v35, v67, v34
	s_and_b64 exec, exec, vcc
	s_cbranch_execz .LBB0_75
	global_load_dwordx4 v[36:39], v70, s[16:17]
	global_load_dwordx4 v[144:147], v70, s[16:17] offset:64
	global_load_dwordx4 v[148:151], v70, s[16:17] offset:128
	global_load_dwordx4 v[152:155], v70, s[16:17] offset:192
	global_load_dwordx4 v[156:159], v70, s[16:17] offset:256
	global_load_dwordx4 v[160:163], v70, s[16:17] offset:320
	global_load_dwordx4 v[176:179], v70, s[16:17] offset:384
	global_load_dwordx4 v[180:183], v70, s[16:17] offset:448
	s_waitcnt lgkmcnt(0)
	v_add_f32_e32 v34, v34, v35
	v_fmamk_f32 v34, v34, 0x3c000000, v208
	v_mul_f32_e32 v35, 0x4b800000, v34
	v_cmp_gt_f32_e32 vcc, s2, v34
	s_nop 1
	v_cndmask_b32_e32 v34, v34, v35, vcc
	v_rsq_f32_e32 v40, v34
	v_lshlrev_b64 v[34:35], 11, v[192:193]
	v_lshl_add_u64 v[34:35], s[86:87], 0, v[34:35]
	v_lshl_add_u64 v[34:35], v[34:35], 0, v[0:1]
	v_mul_f32_e32 v0, 0x45800000, v40
	v_cndmask_b32_e32 v0, v40, v0, vcc
	v_mul_f32_e32 v0, v189, v0
	v_pk_mul_f32 v[30:31], v[30:31], v[0:1] op_sel_hi:[1,0]
	v_pk_mul_f32 v[32:33], v[32:33], v[0:1] op_sel_hi:[1,0]
	v_pk_mul_f32 v[26:27], v[26:27], v[0:1] op_sel_hi:[1,0]
	v_pk_mul_f32 v[28:29], v[28:29], v[0:1] op_sel_hi:[1,0]
	v_pk_mul_f32 v[22:23], v[22:23], v[0:1] op_sel_hi:[1,0]
	v_pk_mul_f32 v[24:25], v[24:25], v[0:1] op_sel_hi:[1,0]
	v_pk_mul_f32 v[18:19], v[18:19], v[0:1] op_sel_hi:[1,0]
	v_pk_mul_f32 v[20:21], v[20:21], v[0:1] op_sel_hi:[1,0]
	v_pk_mul_f32 v[14:15], v[14:15], v[0:1] op_sel_hi:[1,0]
	v_pk_mul_f32 v[16:17], v[16:17], v[0:1] op_sel_hi:[1,0]
	v_pk_mul_f32 v[10:11], v[10:11], v[0:1] op_sel_hi:[1,0]
	v_pk_mul_f32 v[12:13], v[12:13], v[0:1] op_sel_hi:[1,0]
	v_pk_mul_f32 v[6:7], v[6:7], v[0:1] op_sel_hi:[1,0]
	v_pk_mul_f32 v[8:9], v[8:9], v[0:1] op_sel_hi:[1,0]
	v_pk_mul_f32 v[2:3], v[2:3], v[0:1] op_sel_hi:[1,0]
	v_pk_mul_f32 v[4:5], v[4:5], v[0:1] op_sel_hi:[1,0]
	s_waitcnt vmcnt(0)
	v_pk_mul_f32 v[32:33], v[32:33], v[38:39]
	v_pk_mul_f32 v[30:31], v[30:31], v[36:37]
	s_nop 0
	v_cvt_pk_bf16_f32 v30, v30, v31
	v_cvt_pk_bf16_f32 v31, v32, v33
	global_store_dwordx2 v[34:35], v[30:31], off
	v_pk_mul_f32 v[28:29], v[28:29], v[146:147]
	v_pk_mul_f32 v[26:27], v[26:27], v[144:145]
	s_nop 0
	v_cvt_pk_bf16_f32 v26, v26, v27
	v_cvt_pk_bf16_f32 v27, v28, v29
	global_store_dwordx2 v[34:35], v[26:27], off offset:32
	v_pk_mul_f32 v[24:25], v[24:25], v[150:151]
	v_pk_mul_f32 v[22:23], v[22:23], v[148:149]
	s_nop 0
	v_cvt_pk_bf16_f32 v22, v22, v23
	v_cvt_pk_bf16_f32 v23, v24, v25
	global_store_dwordx2 v[34:35], v[22:23], off offset:64
	v_pk_mul_f32 v[20:21], v[20:21], v[154:155]
	v_pk_mul_f32 v[18:19], v[18:19], v[152:153]
	s_nop 0
	v_cvt_pk_bf16_f32 v18, v18, v19
	v_cvt_pk_bf16_f32 v19, v20, v21
	global_store_dwordx2 v[34:35], v[18:19], off offset:96
	v_pk_mul_f32 v[16:17], v[16:17], v[158:159]
	v_pk_mul_f32 v[14:15], v[14:15], v[156:157]
	s_nop 0
	v_cvt_pk_bf16_f32 v14, v14, v15
	v_cvt_pk_bf16_f32 v15, v16, v17
	global_store_dwordx2 v[34:35], v[14:15], off offset:128
	v_pk_mul_f32 v[12:13], v[12:13], v[162:163]
	v_pk_mul_f32 v[10:11], v[10:11], v[160:161]
	s_nop 0
	v_cvt_pk_bf16_f32 v10, v10, v11
	v_cvt_pk_bf16_f32 v11, v12, v13
	global_store_dwordx2 v[34:35], v[10:11], off offset:160
	v_pk_mul_f32 v[8:9], v[8:9], v[178:179]
	v_pk_mul_f32 v[6:7], v[6:7], v[176:177]
	s_nop 0
	v_cvt_pk_bf16_f32 v6, v6, v7
	v_cvt_pk_bf16_f32 v7, v8, v9
	global_store_dwordx2 v[34:35], v[6:7], off offset:192
	v_pk_mul_f32 v[4:5], v[4:5], v[182:183]
	v_pk_mul_f32 v[2:3], v[2:3], v[180:181]
	s_nop 0
	v_cvt_pk_bf16_f32 v2, v2, v3
	v_cvt_pk_bf16_f32 v3, v4, v5
	global_store_dwordx2 v[34:35], v[2:3], off offset:224
	s_branch .LBB0_75
